# vY + one static s_setprio 1 for waves 4-7 at kernel entry (strategy 4, no per-segment flips)
# baseline (speedup 1.0000x reference)
.Lno_remap:
	s_load_dwordx2 s[0:1], s[8:9], 0x4
	s_load_dwordx2 s[76:77], s[92:93], 0x78
	s_waitcnt lgkmcnt(0)
	s_lshl_b32 s36, s33, 3
	s_lshr_b32 s91, s74, 6
	s_cmp_ge_u32 s91, 4
	s_cbranch_scc0 .Lprio_done
	s_setprio 1
.Lprio_done:
	s_lshl_b32 s3, s2, 3
	s_mov_b32 s4, s36
	v_writelane_b32 v252, s76, 0
	s_add_i32 s90, s91, s3
	s_cmpk_gt_i32 s90, 0x4ff
	v_writelane_b32 v252, s77, 1
	v_writelane_b32 v252, s4, 2
	v_and_b32_e32 v2, 63, v1
	s_nop 0
	v_writelane_b32 v252, s5, 3
	s_cbranch_scc1 .LBB0_9
	s_load_dwordx4 s[4:7], s[92:93], 0x10
	s_add_u32 s10, s76, 0x200000
	s_addc_u32 s11, s77, 0
	v_mov_b32_e32 v5, 0
	s_movk_i32 s21, 0x5000
	s_waitcnt lgkmcnt(0)
	s_cmp_lg_u64 s[4:5], 0
	s_cselect_b64 s[12:13], -1, 0
	s_lshl_b32 s3, s90, 6
	s_lshl_b32 s20, s36, 6
	v_lshlrev_b32_e32 v4, 2, v2
	s_mov_b32 s22, 0xa000
	s_mov_b32 s23, 0xf000
	s_mov_b32 s24, 0x14000
	s_mov_b32 s25, 0x19000
	s_mov_b32 s26, 0x1e000
	s_mov_b32 s27, 0x23000
	s_mov_b32 s28, 0x28000
	s_mov_b32 s29, 0x2d000
	s_mov_b32 s30, 0x32000
	s_mov_b32 s31, 0x37000
	s_mov_b32 s34, 0x3c000
	s_mov_b32 s35, 0x41000
	s_mov_b32 s36, 0x46000
	s_mov_b32 s37, 0x4b000
	s_mov_b32 s38, 0x50000
	s_mov_b32 s39, 0x55000
	s_mov_b32 s40, 0x5a000
	s_mov_b32 s41, 0x5f000
	s_mov_b32 s42, 0x64000
	s_mov_b32 s43, 0x69000
	s_mov_b32 s44, 0x6e000
	s_mov_b32 s45, 0x73000
	s_mov_b32 s46, 0x78000
	s_mov_b32 s47, 0x7d000
	s_mov_b32 s48, 0x82000
	s_mov_b32 s49, 0x87000
	s_mov_b32 s50, 0x8c000
	s_mov_b32 s51, 0x91000
	s_mov_b32 s52, 0x96000
	s_mov_b32 s53, 0x9b000
	s_mov_b32 s54, 0xa0000
	s_mov_b32 s55, 0xa5000
	s_mov_b32 s56, 0xaa000
	s_mov_b32 s57, 0xaf000
	s_mov_b32 s59, 0xb4000
	s_mov_b32 s60, 0xb9000
	s_mov_b32 s61, 0xbe000
	s_mov_b32 s62, 0xc3000
	s_mov_b32 s63, 0xc8000
	s_mov_b32 s64, 0xcd000
	s_mov_b32 s65, 0xd2000
	s_mov_b32 s66, 0xd7000
	s_mov_b32 s67, 0xdc000
	s_mov_b32 s68, 0xe1000
	s_mov_b32 s69, 0xe6000
	s_mov_b32 s70, 0xeb000
	s_mov_b32 s71, 0xf0000
	s_mov_b32 s72, 0xf5000
	s_mov_b32 s73, 0xfa000
	s_mov_b32 s76, 0xff000
	s_mov_b32 s77, 0x104000
	s_mov_b32 s78, 0x109000
	s_mov_b32 s79, 0x10e000
	s_mov_b32 s80, 0x113000
	s_mov_b32 s81, 0x118000
	s_mov_b32 s82, 0x11d000
	s_mov_b32 s83, 0x122000
	s_mov_b32 s84, 0x127000
	s_mov_b32 s85, 0x12c000
	s_mov_b32 s86, s90
	s_branch .LBB0_6
